# P5/P6 K-loop MFMA bursts in snake order (each consecutive MFMA pair shares one source operand)
# baseline (speedup 1.0000x reference)
; #define PG8_LDA(dst, b, h) do { if constexpr (FP8) { _Pragma("unroll") for (int m = 0; m < 4; ++m) dst##8[m] = PG8_LD8(PG8_SA(b, h), aoff, aoff1, m); } \
;         else { _Pragma("unroll") for (int m = 0; m < 4; ++m) _Pragma("unroll") for (int k = 0; k < 2; ++k) dst[m][k] = *(const LAS bf16x8*)(lds + PG8_SA(b, h) + (k ? aoff1 : aoff) + m * 2048); } } while (0)
; #define PG8_LDB(dst, b, h) do { if constexpr (FP8) { dst##8[0] = PG8_LD8(PG8_SB(b, h), boff, boff1, 0); dst##8[1] = PG8_LD8(PG8_SB(b, h), boff, boff1, 1); } \
;         else { _Pragma("unroll") for (int n = 0; n < 2; ++n) _Pragma("unroll") for (int k = 0; k < 2; ++k) dst[n][k] = *(const LAS bf16x8*)(lds + PG8_SB(b, h) + (k ? boff1 : boff) + n * 2048); } } while (0)
; #define PG8_WAIT_V(n) asm volatile("s_waitcnt vmcnt(" #n ")" ::: "memory")
; #define PG8_WAIT_L(n) asm volatile("s_waitcnt lgkmcnt(" #n ")" ::: "memory")
; #define PG8_BAR __builtin_amdgcn_s_barrier()
; #define PG8_SCHED __builtin_amdgcn_sched_barrier(0)
; #define PG8_S1 PG8_STAGE(PG8_SA(1, 1), a1 + hstepA, voffA)
; #define PG8_S2 do { PG8_STAGE(PG8_SB(0, 0), b2, voffB); PG8_STAGE(PG8_SB(0, 1), b2 + hstepB, voffB); PG8_STAGE(PG8_SA(0, 0), a2, voffA); } while (0)
; template <class Epi, class SchedT, bool ALIGN_EPI, bool SP2, bool FP8 = false>
; __device__ __forceinline__ void gemm_phase(LAS unsigned char* lds, const Gemm g, const SchedT& S, const Epi& E, const int wid) {
;     ...
;             const bool last = (t == nt - 2);
;             const char* a1 = cA + (size_t)(t + 1) * kstep;
;             const char* a2 = last ? nA : cA + (size_t)(t + 2) * kstep; const char* b2 = last ? nB : cB + (size_t)(t + 2) * kstep;
;             const char* a3 = a2 + kstep; const char* b3 = b2 + kstep;
;             if constexpr (SP2) {
;     ...
;             PG8_LDB(B0, 0, 0); PG8_LDB(B1, 0, 1); PG8_SCHED; PG8_LDA(At, 0, 0); PG8_S1;
;             PG8_WAIT_V(8); PG8_WAIT_L(0); PG8_BAR; PG8_MMAP(0, 0, 0); PG8_BAR; PG8_SCHED;
;             PG8_LDA(At, 0, 1); PG8_S2;
;             PG8_WAIT_V(8); PG8_WAIT_L(0); PG8_BAR; PG8_MMAP(1, 0, 1); PG8_BAR; PG8_SCHED;
.LBB0_899:
	ds_read_b128 v[128:131], v173
	ds_read_b128 v[132:135], v173 offset:1024
	ds_read_b128 v[136:139], v174
	ds_read_b128 v[140:143], v174 offset:1024
	ds_read_b128 v[150:153], v175
	ds_read_b128 v[154:157], v175 offset:1024
	ds_read_b128 v[158:161], v176
	ds_read_b128 v[162:165], v176 offset:1024
	s_add_i32 s35, s34, 2
	s_add_u32 s16, s48, 0xfffc0080
	s_addc_u32 s17, s49, -1
	s_cmp_eq_u32 s27, s34
	s_cselect_b32 s51, s15, s17
	s_cselect_b32 s50, s21, s16
	s_cselect_b32 s53, s24, s31
	s_cselect_b32 s52, s25, s30
	v_mov_b32_e32 v144, v168
	ds_read_b128 v[182:185], v177
	ds_read_b128 v[186:189], v177 offset:1024
	ds_read_b128 v[190:193], v177 offset:2048
	ds_read_b128 v[194:197], v177 offset:3072
	ds_read_b128 v[198:201], v177 offset:4096
	ds_read_b128 v[202:205], v177 offset:5120
	ds_read_b128 v[206:209], v177 offset:6144
	ds_read_b128 v[210:213], v177 offset:7168
	s_add_i32 m0, s87, 0xc000
	s_nop 0
	global_load_lds_dwordx4 v144, s[48:49]
	v_mov_b32_e32 v144, v170
	s_add_i32 m0, s87, 0xe000
	s_nop 0
	global_load_lds_dwordx4 v144, s[48:49]
	s_waitcnt vmcnt(8)
	s_waitcnt lgkmcnt(0)
	s_barrier
	s_setprio 1
	s_waitcnt lgkmcnt(0)
	v_mfma_f32_16x16x32_bf16 v[124:127], v[128:131], v[182:185], v[124:127]
	v_mfma_f32_16x16x32_bf16 v[120:123], v[136:139], v[182:185], v[120:123]
	v_mfma_f32_16x16x32_bf16 v[104:107], v[136:139], v[190:193], v[104:107]
	v_mfma_f32_16x16x32_bf16 v[108:111], v[128:131], v[190:193], v[108:111]
	v_mfma_f32_16x16x32_bf16 v[92:95], v[128:131], v[198:201], v[92:95]
	v_mfma_f32_16x16x32_bf16 v[88:91], v[136:139], v[198:201], v[88:91]
	v_mfma_f32_16x16x32_bf16 v[72:75], v[136:139], v[206:209], v[72:75]
	v_mfma_f32_16x16x32_bf16 v[76:79], v[128:131], v[206:209], v[76:79]
	v_mfma_f32_16x16x32_bf16 v[124:127], v[132:135], v[186:189], v[124:127]
	v_mfma_f32_16x16x32_bf16 v[120:123], v[140:143], v[186:189], v[120:123]
	v_mfma_f32_16x16x32_bf16 v[104:107], v[140:143], v[194:197], v[104:107]
	v_mfma_f32_16x16x32_bf16 v[108:111], v[132:135], v[194:197], v[108:111]
	v_mfma_f32_16x16x32_bf16 v[92:95], v[132:135], v[202:205], v[92:95]
	v_mfma_f32_16x16x32_bf16 v[88:91], v[140:143], v[202:205], v[88:91]
	v_mfma_f32_16x16x32_bf16 v[72:75], v[140:143], v[210:213], v[72:75]
	v_mfma_f32_16x16x32_bf16 v[76:79], v[132:135], v[210:213], v[76:79]
	s_setprio 0
	s_setprio 1
	v_mfma_f32_16x16x32_bf16 v[116:119], v[150:153], v[182:185], v[116:119]
	v_mfma_f32_16x16x32_bf16 v[112:115], v[158:161], v[182:185], v[112:115]
	v_mfma_f32_16x16x32_bf16 v[96:99], v[158:161], v[190:193], v[96:99]
	v_mfma_f32_16x16x32_bf16 v[100:103], v[150:153], v[190:193], v[100:103]
	v_mfma_f32_16x16x32_bf16 v[84:87], v[150:153], v[198:201], v[84:87]
	v_mfma_f32_16x16x32_bf16 v[80:83], v[158:161], v[198:201], v[80:83]
	v_mfma_f32_16x16x32_bf16 v[64:67], v[158:161], v[206:209], v[64:67]
	v_mfma_f32_16x16x32_bf16 v[68:71], v[150:153], v[206:209], v[68:71]
	v_mfma_f32_16x16x32_bf16 v[116:119], v[154:157], v[186:189], v[116:119]
	v_mfma_f32_16x16x32_bf16 v[112:115], v[162:165], v[186:189], v[112:115]
	v_mfma_f32_16x16x32_bf16 v[96:99], v[162:165], v[194:197], v[96:99]
	v_mfma_f32_16x16x32_bf16 v[100:103], v[154:157], v[194:197], v[100:103]
	v_mfma_f32_16x16x32_bf16 v[84:87], v[154:157], v[202:205], v[84:87]
	v_mfma_f32_16x16x32_bf16 v[80:83], v[162:165], v[202:205], v[80:83]
	v_mfma_f32_16x16x32_bf16 v[64:67], v[162:165], v[210:213], v[64:67]
	v_mfma_f32_16x16x32_bf16 v[68:71], v[154:157], v[210:213], v[68:71]
	s_setprio 0
	s_barrier
	v_mov_b32_e32 v144, v169
	s_add_i32 s16, s94, s86
	ds_read_b128 v[182:185], v177 offset:16384
	ds_read_b128 v[186:189], v177 offset:17408
	ds_read_b128 v[190:193], v177 offset:18432
	ds_read_b128 v[194:197], v177 offset:19456
	ds_read_b128 v[198:201], v177 offset:20480
	ds_read_b128 v[202:205], v177 offset:21504
	ds_read_b128 v[206:209], v177 offset:22528
	ds_read_b128 v[210:213], v177 offset:23552
	s_mov_b32 m0, s16
	s_nop 0
	global_load_lds_dwordx4 v144, s[52:53]
	v_mov_b32_e32 v144, v171
	s_add_i32 m0, s16, 0x2000
	s_add_u32 s60, s52, 0x40000
	global_load_lds_dwordx4 v144, s[52:53]
	s_addc_u32 s61, s53, 0
	v_mov_b32_e32 v144, v169
	s_add_i32 s16, s95, s86
	s_mov_b32 m0, s16
	s_nop 0
	global_load_lds_dwordx4 v144, s[60:61]
	v_mov_b32_e32 v144, v171
	s_add_i32 m0, s16, 0x2000
	s_nop 0
	global_load_lds_dwordx4 v144, s[60:61]
	v_mov_b32_e32 v144, v168
	s_mov_b32 m0, s87
	s_nop 0
	global_load_lds_dwordx4 v144, s[50:51]
	v_mov_b32_e32 v144, v170
	s_mov_b32 m0, s88
	s_nop 0
	global_load_lds_dwordx4 v144, s[50:51]
	s_waitcnt vmcnt(8)
	s_waitcnt lgkmcnt(0)
	s_barrier
; #define PG8_LDA(dst, b, h) do { if constexpr (FP8) { _Pragma("unroll") for (int m = 0; m < 4; ++m) dst##8[m] = PG8_LD8(PG8_SA(b, h), aoff, aoff1, m); } \
;         else { _Pragma("unroll") for (int m = 0; m < 4; ++m) _Pragma("unroll") for (int k = 0; k < 2; ++k) dst[m][k] = *(const LAS bf16x8*)(lds + PG8_SA(b, h) + (k ? aoff1 : aoff) + m * 2048); } } while (0)
; #define PG8_LDB(dst, b, h) do { if constexpr (FP8) { dst##8[0] = PG8_LD8(PG8_SB(b, h), boff, boff1, 0); dst##8[1] = PG8_LD8(PG8_SB(b, h), boff, boff1, 1); } \
;         else { _Pragma("unroll") for (int n = 0; n < 2; ++n) _Pragma("unroll") for (int k = 0; k < 2; ++k) dst[n][k] = *(const LAS bf16x8*)(lds + PG8_SB(b, h) + (k ? boff1 : boff) + n * 2048); } } while (0)
; #define PG8_WAIT_V(n) asm volatile("s_waitcnt vmcnt(" #n ")" ::: "memory")
; #define PG8_WAIT_L(n) asm volatile("s_waitcnt lgkmcnt(" #n ")" ::: "memory")
; #define PG8_BAR __builtin_amdgcn_s_barrier()
; #define PG8_SCHED __builtin_amdgcn_sched_barrier(0)
; #define PG8_S3 PG8_STAGE(PG8_SA(0, 1), a2 + hstepA, voffA)
; template <class Epi, class SchedT, bool ALIGN_EPI, bool SP2, bool FP8 = false>
; __device__ __forceinline__ void gemm_phase(LAS unsigned char* lds, const Gemm g, const SchedT& S, const Epi& E, const int wid) {
;     ...
;             PG8_WAIT_V(8); PG8_WAIT_L(0); PG8_BAR; PG8_MMAP(1, 0, 1); PG8_BAR; PG8_SCHED;
;             PG8_LDB(B0, 1, 0); PG8_LDB(B1, 1, 1); PG8_SCHED; PG8_LDA(At, 1, 0); PG8_S3;
;             PG8_WAIT_V(8); PG8_WAIT_L(0); PG8_BAR; PG8_MMAP(0, 1, 0); PG8_BAR; PG8_SCHED;
	s_setprio 1
	s_waitcnt lgkmcnt(0)
	v_mfma_f32_16x16x32_bf16 v[60:63], v[128:131], v[182:185], v[60:63]
	v_mfma_f32_16x16x32_bf16 v[56:59], v[136:139], v[182:185], v[56:59]
	v_mfma_f32_16x16x32_bf16 v[40:43], v[136:139], v[190:193], v[40:43]
	v_mfma_f32_16x16x32_bf16 v[44:47], v[128:131], v[190:193], v[44:47]
	v_mfma_f32_16x16x32_bf16 v[28:31], v[128:131], v[198:201], v[28:31]
	v_mfma_f32_16x16x32_bf16 v[24:27], v[136:139], v[198:201], v[24:27]
	v_mfma_f32_16x16x32_bf16 v[8:11], v[136:139], v[206:209], v[8:11]
	v_mfma_f32_16x16x32_bf16 v[12:15], v[128:131], v[206:209], v[12:15]
	v_mfma_f32_16x16x32_bf16 v[60:63], v[132:135], v[186:189], v[60:63]
	v_mfma_f32_16x16x32_bf16 v[56:59], v[140:143], v[186:189], v[56:59]
	v_mfma_f32_16x16x32_bf16 v[40:43], v[140:143], v[194:197], v[40:43]
	v_mfma_f32_16x16x32_bf16 v[44:47], v[132:135], v[194:197], v[44:47]
	v_mfma_f32_16x16x32_bf16 v[28:31], v[132:135], v[202:205], v[28:31]
	v_mfma_f32_16x16x32_bf16 v[24:27], v[140:143], v[202:205], v[24:27]
	v_mfma_f32_16x16x32_bf16 v[8:11], v[140:143], v[210:213], v[8:11]
	v_mfma_f32_16x16x32_bf16 v[12:15], v[132:135], v[210:213], v[12:15]
	s_setprio 0
	s_setprio 1
	v_mfma_f32_16x16x32_bf16 v[52:55], v[150:153], v[182:185], v[52:55]
	v_mfma_f32_16x16x32_bf16 v[48:51], v[158:161], v[182:185], v[48:51]
	v_mfma_f32_16x16x32_bf16 v[32:35], v[158:161], v[190:193], v[32:35]
	v_mfma_f32_16x16x32_bf16 v[36:39], v[150:153], v[190:193], v[36:39]
	v_mfma_f32_16x16x32_bf16 v[20:23], v[150:153], v[198:201], v[20:23]
	v_mfma_f32_16x16x32_bf16 v[16:19], v[158:161], v[198:201], v[16:19]
	v_mfma_f32_16x16x32_bf16 v[0:3], v[158:161], v[206:209], v[0:3]
	v_mfma_f32_16x16x32_bf16 v[4:7], v[150:153], v[206:209], v[4:7]
	v_mfma_f32_16x16x32_bf16 v[52:55], v[154:157], v[186:189], v[52:55]
	v_mfma_f32_16x16x32_bf16 v[48:51], v[162:165], v[186:189], v[48:51]
	v_mfma_f32_16x16x32_bf16 v[32:35], v[162:165], v[194:197], v[32:35]
	v_mfma_f32_16x16x32_bf16 v[36:39], v[154:157], v[194:197], v[36:39]
	v_mfma_f32_16x16x32_bf16 v[20:23], v[154:157], v[202:205], v[20:23]
	v_mfma_f32_16x16x32_bf16 v[16:19], v[162:165], v[202:205], v[16:19]
	v_mfma_f32_16x16x32_bf16 v[0:3], v[162:165], v[210:213], v[0:3]
	v_mfma_f32_16x16x32_bf16 v[4:7], v[154:157], v[210:213], v[4:7]
	s_setprio 0
	s_barrier
	s_add_i32 s16, 0, 0x18000
	s_add_i32 s17, 0, 0x1c000
	v_add_u32_e32 v132, s16, v172
	v_add_u32_e32 v144, s17, v172
	ds_read_b128 v[128:131], v132
	ds_read_b128 v[132:135], v132 offset:1024
	ds_read_b128 v[136:139], v178
	ds_read_b128 v[140:143], v178 offset:1024
	ds_read_b128 v[150:153], v144
	ds_read_b128 v[154:157], v144 offset:1024
	ds_read_b128 v[158:161], v179
	ds_read_b128 v[162:165], v179 offset:1024
	s_add_u32 s60, s50, 0x40000
	v_mov_b32_e32 v144, v168
	s_mov_b32 m0, s89
	ds_read_b128 v[182:185], v177 offset:32768
	ds_read_b128 v[186:189], v177 offset:33792
	ds_read_b128 v[190:193], v177 offset:34816
	ds_read_b128 v[194:197], v177 offset:35840
	ds_read_b128 v[198:201], v177 offset:36864
	ds_read_b128 v[202:205], v177 offset:37888
	ds_read_b128 v[206:209], v177 offset:38912
	ds_read_b128 v[210:213], v177 offset:39936
	s_addc_u32 s61, s51, 0
	s_nop 0
	global_load_lds_dwordx4 v144, s[60:61]
	v_mov_b32_e32 v144, v170
	s_mov_b32 m0, s90
	s_nop 0
	global_load_lds_dwordx4 v144, s[60:61]
	s_waitcnt vmcnt(8)
	s_waitcnt lgkmcnt(0)
	s_barrier
	s_setprio 1
	s_waitcnt lgkmcnt(0)
	v_mfma_f32_16x16x32_bf16 v[124:127], v[128:131], v[182:185], v[124:127]
	v_mfma_f32_16x16x32_bf16 v[120:123], v[136:139], v[182:185], v[120:123]
	v_mfma_f32_16x16x32_bf16 v[104:107], v[136:139], v[190:193], v[104:107]
	v_mfma_f32_16x16x32_bf16 v[108:111], v[128:131], v[190:193], v[108:111]
	v_mfma_f32_16x16x32_bf16 v[92:95], v[128:131], v[198:201], v[92:95]
	v_mfma_f32_16x16x32_bf16 v[88:91], v[136:139], v[198:201], v[88:91]
	v_mfma_f32_16x16x32_bf16 v[72:75], v[136:139], v[206:209], v[72:75]
	v_mfma_f32_16x16x32_bf16 v[76:79], v[128:131], v[206:209], v[76:79]
	v_mfma_f32_16x16x32_bf16 v[124:127], v[132:135], v[186:189], v[124:127]
	v_mfma_f32_16x16x32_bf16 v[120:123], v[140:143], v[186:189], v[120:123]
	v_mfma_f32_16x16x32_bf16 v[104:107], v[140:143], v[194:197], v[104:107]
	v_mfma_f32_16x16x32_bf16 v[108:111], v[132:135], v[194:197], v[108:111]
	v_mfma_f32_16x16x32_bf16 v[92:95], v[132:135], v[202:205], v[92:95]
	v_mfma_f32_16x16x32_bf16 v[88:91], v[140:143], v[202:205], v[88:91]
	v_mfma_f32_16x16x32_bf16 v[72:75], v[140:143], v[210:213], v[72:75]
	v_mfma_f32_16x16x32_bf16 v[76:79], v[132:135], v[210:213], v[76:79]
	s_setprio 0
	s_setprio 1
	v_mfma_f32_16x16x32_bf16 v[116:119], v[150:153], v[182:185], v[116:119]
	v_mfma_f32_16x16x32_bf16 v[112:115], v[158:161], v[182:185], v[112:115]
	v_mfma_f32_16x16x32_bf16 v[96:99], v[158:161], v[190:193], v[96:99]
	v_mfma_f32_16x16x32_bf16 v[100:103], v[150:153], v[190:193], v[100:103]
	v_mfma_f32_16x16x32_bf16 v[84:87], v[150:153], v[198:201], v[84:87]
	v_mfma_f32_16x16x32_bf16 v[80:83], v[158:161], v[198:201], v[80:83]
	v_mfma_f32_16x16x32_bf16 v[64:67], v[158:161], v[206:209], v[64:67]
	v_mfma_f32_16x16x32_bf16 v[68:71], v[150:153], v[206:209], v[68:71]
	v_mfma_f32_16x16x32_bf16 v[116:119], v[154:157], v[186:189], v[116:119]
	v_mfma_f32_16x16x32_bf16 v[112:115], v[162:165], v[186:189], v[112:115]
	v_mfma_f32_16x16x32_bf16 v[96:99], v[162:165], v[194:197], v[96:99]
	v_mfma_f32_16x16x32_bf16 v[100:103], v[154:157], v[194:197], v[100:103]
	v_mfma_f32_16x16x32_bf16 v[84:87], v[154:157], v[202:205], v[84:87]
	v_mfma_f32_16x16x32_bf16 v[80:83], v[162:165], v[202:205], v[80:83]
	v_mfma_f32_16x16x32_bf16 v[64:67], v[162:165], v[210:213], v[64:67]
	v_mfma_f32_16x16x32_bf16 v[68:71], v[154:157], v[210:213], v[68:71]
	s_setprio 0
	s_barrier
; #define PG8_LDA(dst, b, h) do { if constexpr (FP8) { _Pragma("unroll") for (int m = 0; m < 4; ++m) dst##8[m] = PG8_LD8(PG8_SA(b, h), aoff, aoff1, m); } \
;         else { _Pragma("unroll") for (int m = 0; m < 4; ++m) _Pragma("unroll") for (int k = 0; k < 2; ++k) dst[m][k] = *(const LAS bf16x8*)(lds + PG8_SA(b, h) + (k ? aoff1 : aoff) + m * 2048); } } while (0)
; #define PG8_WAIT_V(n) asm volatile("s_waitcnt vmcnt(" #n ")" ::: "memory")
; #define PG8_WAIT_L(n) asm volatile("s_waitcnt lgkmcnt(" #n ")" ::: "memory")
; #define PG8_BAR __builtin_amdgcn_s_barrier()
; #define PG8_SCHED __builtin_amdgcn_sched_barrier(0)
; #define PG8_S4 do { PG8_STAGE(PG8_SB(1, 0), b3, voffB); PG8_STAGE(PG8_SB(1, 1), b3 + hstepB, voffB); PG8_STAGE(PG8_SA(1, 0), a3, voffA); } while (0)
; template <class Epi, class SchedT, bool ALIGN_EPI, bool SP2, bool FP8 = false>
; __device__ __forceinline__ void gemm_phase(LAS unsigned char* lds, const Gemm g, const SchedT& S, const Epi& E, const int wid) {
;     ...
;         for (int t = 0; t < nt; t += 2) {
;     ...
;             PG8_LDA(At, 1, 1); PG8_S4;
;             PG8_WAIT_V(8); PG8_WAIT_L(0); PG8_BAR; PG8_MMAP(1, 1, 1); PG8_BAR; PG8_SCHED;
	v_mov_b32_e32 v144, v169
	ds_read_b128 v[182:185], v177 offset:49152
	ds_read_b128 v[186:189], v177 offset:50176
	ds_read_b128 v[190:193], v177 offset:51200
	ds_read_b128 v[194:197], v177 offset:52224
	ds_read_b128 v[198:201], v177 offset:53248
	ds_read_b128 v[202:205], v177 offset:54272
	ds_read_b128 v[206:209], v177 offset:55296
	ds_read_b128 v[210:213], v177 offset:56320
	s_add_i32 s16, s16, s86
	v_lshl_add_u64 v[166:167], s[52:53], 0, v[144:145]
	v_lshl_add_u64 v[166:167], v[166:167], 0, s[6:7]
	s_mov_b32 m0, s16
	v_mov_b32_e32 v144, v171
	global_load_lds_dwordx4 v[166:167], off
	s_add_i32 m0, s16, 0x2000
	s_nop 0
	v_lshl_add_u64 v[166:167], s[52:53], 0, v[144:145]
	s_add_u32 s52, s52, 0x40080
	v_lshl_add_u64 v[166:167], v[166:167], 0, s[6:7]
	s_addc_u32 s53, s53, 0
	v_mov_b32_e32 v144, v169
	s_add_i32 s16, s17, s86
	global_load_lds_dwordx4 v[166:167], off
	s_mov_b32 m0, s16
	s_nop 0
	global_load_lds_dwordx4 v144, s[52:53]
	v_mov_b32_e32 v144, v171
	s_add_i32 m0, s16, 0x2000
	s_nop 0
	global_load_lds_dwordx4 v144, s[52:53]
	v_mov_b32_e32 v144, v168
	s_mov_b32 m0, s92
	v_lshl_add_u64 v[166:167], s[50:51], 0, v[144:145]
	v_lshl_add_u64 v[166:167], v[166:167], 0, s[6:7]
	v_mov_b32_e32 v144, v170
	global_load_lds_dwordx4 v[166:167], off
	s_mov_b32 m0, s93
	v_lshl_add_u64 v[166:167], s[50:51], 0, v[144:145]
	v_lshl_add_u64 v[166:167], v[166:167], 0, s[6:7]
	global_load_lds_dwordx4 v[166:167], off
	s_waitcnt vmcnt(8)
	s_waitcnt lgkmcnt(0)
	s_barrier
	s_setprio 1
	s_waitcnt lgkmcnt(0)
	v_mfma_f32_16x16x32_bf16 v[60:63], v[128:131], v[182:185], v[60:63]
	v_mfma_f32_16x16x32_bf16 v[56:59], v[136:139], v[182:185], v[56:59]
	v_mfma_f32_16x16x32_bf16 v[40:43], v[136:139], v[190:193], v[40:43]
	v_mfma_f32_16x16x32_bf16 v[44:47], v[128:131], v[190:193], v[44:47]
	v_mfma_f32_16x16x32_bf16 v[28:31], v[128:131], v[198:201], v[28:31]
	v_mfma_f32_16x16x32_bf16 v[24:27], v[136:139], v[198:201], v[24:27]
	v_mfma_f32_16x16x32_bf16 v[8:11], v[136:139], v[206:209], v[8:11]
	v_mfma_f32_16x16x32_bf16 v[12:15], v[128:131], v[206:209], v[12:15]
	v_mfma_f32_16x16x32_bf16 v[60:63], v[132:135], v[186:189], v[60:63]
	v_mfma_f32_16x16x32_bf16 v[56:59], v[140:143], v[186:189], v[56:59]
	v_mfma_f32_16x16x32_bf16 v[40:43], v[140:143], v[194:197], v[40:43]
	v_mfma_f32_16x16x32_bf16 v[44:47], v[132:135], v[194:197], v[44:47]
	v_mfma_f32_16x16x32_bf16 v[28:31], v[132:135], v[202:205], v[28:31]
	v_mfma_f32_16x16x32_bf16 v[24:27], v[140:143], v[202:205], v[24:27]
	v_mfma_f32_16x16x32_bf16 v[8:11], v[140:143], v[210:213], v[8:11]
	v_mfma_f32_16x16x32_bf16 v[12:15], v[132:135], v[210:213], v[12:15]
	s_setprio 0
	s_setprio 1
	v_mfma_f32_16x16x32_bf16 v[52:55], v[150:153], v[182:185], v[52:55]
	v_mfma_f32_16x16x32_bf16 v[48:51], v[158:161], v[182:185], v[48:51]
	v_mfma_f32_16x16x32_bf16 v[32:35], v[158:161], v[190:193], v[32:35]
	v_mfma_f32_16x16x32_bf16 v[36:39], v[150:153], v[190:193], v[36:39]
	v_mfma_f32_16x16x32_bf16 v[20:23], v[150:153], v[198:201], v[20:23]
	v_mfma_f32_16x16x32_bf16 v[16:19], v[158:161], v[198:201], v[16:19]
	v_mfma_f32_16x16x32_bf16 v[0:3], v[158:161], v[206:209], v[0:3]
	v_mfma_f32_16x16x32_bf16 v[4:7], v[150:153], v[206:209], v[4:7]
	v_mfma_f32_16x16x32_bf16 v[52:55], v[154:157], v[186:189], v[52:55]
	v_mfma_f32_16x16x32_bf16 v[48:51], v[162:165], v[186:189], v[48:51]
	v_mfma_f32_16x16x32_bf16 v[32:35], v[162:165], v[194:197], v[32:35]
	v_mfma_f32_16x16x32_bf16 v[36:39], v[154:157], v[194:197], v[36:39]
	v_mfma_f32_16x16x32_bf16 v[20:23], v[154:157], v[202:205], v[20:23]
	v_mfma_f32_16x16x32_bf16 v[16:19], v[162:165], v[202:205], v[16:19]
	v_mfma_f32_16x16x32_bf16 v[0:3], v[162:165], v[210:213], v[0:3]
	v_mfma_f32_16x16x32_bf16 v[4:7], v[154:157], v[210:213], v[4:7]
	s_setprio 0
	s_barrier
	s_add_u32 s48, s48, 0x100
	s_addc_u32 s49, s49, 0
	s_add_u32 s30, s30, 0x100
	s_addc_u32 s31, s31, 0
	s_cmp_ge_i32 s35, s20
	s_mov_b32 s34, s35
	s_cbranch_scc0 .LBB0_899
	s_branch .LBB0_894

; #define PG8_LDA(dst, b, h) do { if constexpr (FP8) { _Pragma("unroll") for (int m = 0; m < 4; ++m) dst##8[m] = PG8_LD8(PG8_SA(b, h), aoff, aoff1, m); } \
;         else { _Pragma("unroll") for (int m = 0; m < 4; ++m) _Pragma("unroll") for (int k = 0; k < 2; ++k) dst[m][k] = *(const LAS bf16x8*)(lds + PG8_SA(b, h) + (k ? aoff1 : aoff) + m * 2048); } } while (0)
; #define PG8_LDB(dst, b, h) do { if constexpr (FP8) { dst##8[0] = PG8_LD8(PG8_SB(b, h), boff, boff1, 0); dst##8[1] = PG8_LD8(PG8_SB(b, h), boff, boff1, 1); } \
;         else { _Pragma("unroll") for (int n = 0; n < 2; ++n) _Pragma("unroll") for (int k = 0; k < 2; ++k) dst[n][k] = *(const LAS bf16x8*)(lds + PG8_SB(b, h) + (k ? boff1 : boff) + n * 2048); } } while (0)
; #define PG8_WAIT_V(n) asm volatile("s_waitcnt vmcnt(" #n ")" ::: "memory")
; #define PG8_WAIT_L(n) asm volatile("s_waitcnt lgkmcnt(" #n ")" ::: "memory")
; #define PG8_BAR __builtin_amdgcn_s_barrier()
; #define PG8_SCHED __builtin_amdgcn_sched_barrier(0)
; #define PG8_S1 PG8_STAGE(PG8_SA(1, 1), a1 + hstepA, voffA)
; #define PG8_S2 do { PG8_STAGE(PG8_SB(0, 0), b2, voffB); PG8_STAGE(PG8_SB(0, 1), b2 + hstepB, voffB); PG8_STAGE(PG8_SA(0, 0), a2, voffA); } while (0)
; template <class Epi, class SchedT, bool ALIGN_EPI, bool SP2, bool FP8 = false>
; __device__ __forceinline__ void gemm_phase(LAS unsigned char* lds, const Gemm g, const SchedT& S, const Epi& E, const int wid) {
;     ...
;             const bool last = (t == nt - 2);
;             const char* a1 = cA + (size_t)(t + 1) * kstep;
;             const char* a2 = last ? nA : cA + (size_t)(t + 2) * kstep; const char* b2 = last ? nB : cB + (size_t)(t + 2) * kstep;
;             const char* a3 = a2 + kstep; const char* b3 = b2 + kstep;
;             if constexpr (SP2) {
;     ...
;             PG8_LDB(B0, 0, 0); PG8_LDB(B1, 0, 1); PG8_SCHED; PG8_LDA(At, 0, 0); PG8_S1;
;             PG8_WAIT_V(8); PG8_WAIT_L(0); PG8_BAR; PG8_MMAP(0, 0, 0); PG8_BAR; PG8_SCHED;
;             PG8_LDA(At, 0, 1); PG8_S2;
;             PG8_WAIT_V(8); PG8_WAIT_L(0); PG8_BAR; PG8_MMAP(1, 0, 1); PG8_BAR; PG8_SCHED;
.LBB0_970:
	ds_read_b128 v[134:137], v175
	ds_read_b128 v[138:141], v175 offset:1024
	ds_read_b128 v[142:145], v176
	ds_read_b128 v[146:149], v176 offset:1024
	ds_read_b128 v[150:153], v177
	ds_read_b128 v[154:157], v177 offset:1024
	ds_read_b128 v[158:161], v178
	ds_read_b128 v[162:165], v178 offset:1024
	s_add_i32 s48, s34, 2
	s_add_u32 s16, s24, 0xfff00080
	s_addc_u32 s17, s25, -1
	s_cmp_eq_u32 s45, s34
	s_cselect_b32 s34, s15, s16
	s_cselect_b32 s35, s13, s17
	s_cselect_b32 s39, s27, s47
	s_cselect_b32 s38, s31, s46
	v_mov_b32_e32 v128, v172
	ds_read_b128 v[166:169], v179
	ds_read_b128 v[184:187], v179 offset:1024
	ds_read_b128 v[188:191], v179 offset:2048
	ds_read_b128 v[192:195], v179 offset:3072
	ds_read_b128 v[196:199], v179 offset:4096
	ds_read_b128 v[200:203], v179 offset:5120
	ds_read_b128 v[204:207], v179 offset:6144
	ds_read_b128 v[208:211], v179 offset:7168
	s_add_i32 m0, s87, 0xc000
	s_nop 0
	global_load_lds_dwordx4 v128, s[24:25]
	v_mov_b32_e32 v128, v173
	s_add_i32 m0, s87, 0xe000
	s_nop 0
	global_load_lds_dwordx4 v128, s[24:25]
	s_waitcnt vmcnt(8)
	s_waitcnt lgkmcnt(0)
	s_barrier
	s_setprio 1
	s_waitcnt lgkmcnt(0)
	v_mfma_f32_16x16x32_bf16 v[124:127], v[134:137], v[166:169], v[124:127]
	v_mfma_f32_16x16x32_bf16 v[120:123], v[142:145], v[166:169], v[120:123]
	v_mfma_f32_16x16x32_bf16 v[104:107], v[142:145], v[188:191], v[104:107]
	v_mfma_f32_16x16x32_bf16 v[108:111], v[134:137], v[188:191], v[108:111]
	v_mfma_f32_16x16x32_bf16 v[92:95], v[134:137], v[196:199], v[92:95]
	v_mfma_f32_16x16x32_bf16 v[88:91], v[142:145], v[196:199], v[88:91]
	v_mfma_f32_16x16x32_bf16 v[72:75], v[142:145], v[204:207], v[72:75]
	v_mfma_f32_16x16x32_bf16 v[76:79], v[134:137], v[204:207], v[76:79]
	v_mfma_f32_16x16x32_bf16 v[124:127], v[138:141], v[184:187], v[124:127]
	v_mfma_f32_16x16x32_bf16 v[120:123], v[146:149], v[184:187], v[120:123]
	v_mfma_f32_16x16x32_bf16 v[104:107], v[146:149], v[192:195], v[104:107]
	v_mfma_f32_16x16x32_bf16 v[108:111], v[138:141], v[192:195], v[108:111]
	v_mfma_f32_16x16x32_bf16 v[92:95], v[138:141], v[200:203], v[92:95]
	v_mfma_f32_16x16x32_bf16 v[88:91], v[146:149], v[200:203], v[88:91]
	v_mfma_f32_16x16x32_bf16 v[72:75], v[146:149], v[208:211], v[72:75]
	v_mfma_f32_16x16x32_bf16 v[76:79], v[138:141], v[208:211], v[76:79]
	s_setprio 0
	s_setprio 1
	v_mfma_f32_16x16x32_bf16 v[116:119], v[150:153], v[166:169], v[116:119]
	v_mfma_f32_16x16x32_bf16 v[112:115], v[158:161], v[166:169], v[112:115]
	v_mfma_f32_16x16x32_bf16 v[96:99], v[158:161], v[188:191], v[96:99]
	v_mfma_f32_16x16x32_bf16 v[100:103], v[150:153], v[188:191], v[100:103]
	v_mfma_f32_16x16x32_bf16 v[84:87], v[150:153], v[196:199], v[84:87]
	v_mfma_f32_16x16x32_bf16 v[80:83], v[158:161], v[196:199], v[80:83]
	v_mfma_f32_16x16x32_bf16 v[64:67], v[158:161], v[204:207], v[64:67]
	v_mfma_f32_16x16x32_bf16 v[68:71], v[150:153], v[204:207], v[68:71]
	v_mfma_f32_16x16x32_bf16 v[116:119], v[154:157], v[184:187], v[116:119]
	v_mfma_f32_16x16x32_bf16 v[112:115], v[162:165], v[184:187], v[112:115]
	v_mfma_f32_16x16x32_bf16 v[96:99], v[162:165], v[192:195], v[96:99]
	v_mfma_f32_16x16x32_bf16 v[100:103], v[154:157], v[192:195], v[100:103]
	v_mfma_f32_16x16x32_bf16 v[84:87], v[154:157], v[200:203], v[84:87]
	v_mfma_f32_16x16x32_bf16 v[80:83], v[162:165], v[200:203], v[80:83]
	v_mfma_f32_16x16x32_bf16 v[64:67], v[162:165], v[208:211], v[64:67]
	v_mfma_f32_16x16x32_bf16 v[68:71], v[154:157], v[208:211], v[68:71]
	s_setprio 0
	s_barrier
	v_mov_b32_e32 v128, v172
	s_add_i32 s16, s94, s86
	ds_read_b128 v[166:169], v179 offset:16384
	ds_read_b128 v[184:187], v179 offset:17408
	ds_read_b128 v[188:191], v179 offset:18432
	ds_read_b128 v[192:195], v179 offset:19456
	ds_read_b128 v[196:199], v179 offset:20480
	ds_read_b128 v[200:203], v179 offset:21504
	ds_read_b128 v[204:207], v179 offset:22528
	ds_read_b128 v[208:211], v179 offset:23552
	s_mov_b32 m0, s16
	s_nop 0
	global_load_lds_dwordx4 v128, s[38:39]
	v_mov_b32_e32 v128, v173
	s_add_i32 m0, s16, 0x2000
	s_add_u32 s50, s38, 0x100000
	global_load_lds_dwordx4 v128, s[38:39]
	s_addc_u32 s51, s39, 0
	v_mov_b32_e32 v128, v172
	s_add_i32 s16, s95, s86
	s_mov_b32 m0, s16
	s_nop 0
	global_load_lds_dwordx4 v128, s[50:51]
	v_mov_b32_e32 v128, v173
	s_add_i32 m0, s16, 0x2000
	s_nop 0
	global_load_lds_dwordx4 v128, s[50:51]
	v_mov_b32_e32 v128, v172
	s_mov_b32 m0, s87
	s_nop 0
	global_load_lds_dwordx4 v128, s[34:35]
	v_mov_b32_e32 v128, v173
	s_mov_b32 m0, s88
	s_nop 0
	global_load_lds_dwordx4 v128, s[34:35]
	s_waitcnt vmcnt(8)
	s_waitcnt lgkmcnt(0)
	s_barrier
; #define PG8_LDA(dst, b, h) do { if constexpr (FP8) { _Pragma("unroll") for (int m = 0; m < 4; ++m) dst##8[m] = PG8_LD8(PG8_SA(b, h), aoff, aoff1, m); } \
;         else { _Pragma("unroll") for (int m = 0; m < 4; ++m) _Pragma("unroll") for (int k = 0; k < 2; ++k) dst[m][k] = *(const LAS bf16x8*)(lds + PG8_SA(b, h) + (k ? aoff1 : aoff) + m * 2048); } } while (0)
; #define PG8_LDB(dst, b, h) do { if constexpr (FP8) { dst##8[0] = PG8_LD8(PG8_SB(b, h), boff, boff1, 0); dst##8[1] = PG8_LD8(PG8_SB(b, h), boff, boff1, 1); } \
;         else { _Pragma("unroll") for (int n = 0; n < 2; ++n) _Pragma("unroll") for (int k = 0; k < 2; ++k) dst[n][k] = *(const LAS bf16x8*)(lds + PG8_SB(b, h) + (k ? boff1 : boff) + n * 2048); } } while (0)
; #define PG8_WAIT_V(n) asm volatile("s_waitcnt vmcnt(" #n ")" ::: "memory")
; #define PG8_WAIT_L(n) asm volatile("s_waitcnt lgkmcnt(" #n ")" ::: "memory")
; #define PG8_BAR __builtin_amdgcn_s_barrier()
; #define PG8_SCHED __builtin_amdgcn_sched_barrier(0)
; #define PG8_S3 PG8_STAGE(PG8_SA(0, 1), a2 + hstepA, voffA)
; template <class Epi, class SchedT, bool ALIGN_EPI, bool SP2, bool FP8 = false>
; __device__ __forceinline__ void gemm_phase(LAS unsigned char* lds, const Gemm g, const SchedT& S, const Epi& E, const int wid) {
;     ...
;             PG8_WAIT_V(8); PG8_WAIT_L(0); PG8_BAR; PG8_MMAP(1, 0, 1); PG8_BAR; PG8_SCHED;
;             PG8_LDB(B0, 1, 0); PG8_LDB(B1, 1, 1); PG8_SCHED; PG8_LDA(At, 1, 0); PG8_S3;
;             PG8_WAIT_V(8); PG8_WAIT_L(0); PG8_BAR; PG8_MMAP(0, 1, 0); PG8_BAR; PG8_SCHED;
	s_setprio 1
	s_waitcnt lgkmcnt(0)
	v_mfma_f32_16x16x32_bf16 v[60:63], v[134:137], v[166:169], v[60:63]
	v_mfma_f32_16x16x32_bf16 v[56:59], v[142:145], v[166:169], v[56:59]
	v_mfma_f32_16x16x32_bf16 v[40:43], v[142:145], v[188:191], v[40:43]
	v_mfma_f32_16x16x32_bf16 v[44:47], v[134:137], v[188:191], v[44:47]
	v_mfma_f32_16x16x32_bf16 v[28:31], v[134:137], v[196:199], v[28:31]
	v_mfma_f32_16x16x32_bf16 v[24:27], v[142:145], v[196:199], v[24:27]
	v_mfma_f32_16x16x32_bf16 v[8:11], v[142:145], v[204:207], v[8:11]
	v_mfma_f32_16x16x32_bf16 v[12:15], v[134:137], v[204:207], v[12:15]
	v_mfma_f32_16x16x32_bf16 v[60:63], v[138:141], v[184:187], v[60:63]
	v_mfma_f32_16x16x32_bf16 v[56:59], v[146:149], v[184:187], v[56:59]
	v_mfma_f32_16x16x32_bf16 v[40:43], v[146:149], v[192:195], v[40:43]
	v_mfma_f32_16x16x32_bf16 v[44:47], v[138:141], v[192:195], v[44:47]
	v_mfma_f32_16x16x32_bf16 v[28:31], v[138:141], v[200:203], v[28:31]
	v_mfma_f32_16x16x32_bf16 v[24:27], v[146:149], v[200:203], v[24:27]
	v_mfma_f32_16x16x32_bf16 v[8:11], v[146:149], v[208:211], v[8:11]
	v_mfma_f32_16x16x32_bf16 v[12:15], v[138:141], v[208:211], v[12:15]
	s_setprio 0
	s_setprio 1
	v_mfma_f32_16x16x32_bf16 v[52:55], v[150:153], v[166:169], v[52:55]
	v_mfma_f32_16x16x32_bf16 v[48:51], v[158:161], v[166:169], v[48:51]
	v_mfma_f32_16x16x32_bf16 v[32:35], v[158:161], v[188:191], v[32:35]
	v_mfma_f32_16x16x32_bf16 v[36:39], v[150:153], v[188:191], v[36:39]
	v_mfma_f32_16x16x32_bf16 v[20:23], v[150:153], v[196:199], v[20:23]
	v_mfma_f32_16x16x32_bf16 v[16:19], v[158:161], v[196:199], v[16:19]
	v_mfma_f32_16x16x32_bf16 v[0:3], v[158:161], v[204:207], v[0:3]
	v_mfma_f32_16x16x32_bf16 v[4:7], v[150:153], v[204:207], v[4:7]
	v_mfma_f32_16x16x32_bf16 v[52:55], v[154:157], v[184:187], v[52:55]
	v_mfma_f32_16x16x32_bf16 v[48:51], v[162:165], v[184:187], v[48:51]
	v_mfma_f32_16x16x32_bf16 v[32:35], v[162:165], v[192:195], v[32:35]
	v_mfma_f32_16x16x32_bf16 v[36:39], v[154:157], v[192:195], v[36:39]
	v_mfma_f32_16x16x32_bf16 v[20:23], v[154:157], v[200:203], v[20:23]
	v_mfma_f32_16x16x32_bf16 v[16:19], v[162:165], v[200:203], v[16:19]
	v_mfma_f32_16x16x32_bf16 v[0:3], v[162:165], v[208:211], v[0:3]
	v_mfma_f32_16x16x32_bf16 v[4:7], v[154:157], v[208:211], v[4:7]
	s_setprio 0
	s_barrier
	s_add_i32 s16, 0, 0x18000
	v_add_u32_e32 v128, s16, v174
	s_add_i32 s17, 0, 0x1c000
	ds_read_b128 v[134:137], v128
	ds_read_b128 v[138:141], v128 offset:1024
	ds_read_b128 v[142:145], v180
	ds_read_b128 v[146:149], v180 offset:1024
	v_add_u32_e32 v128, s17, v174
	ds_read_b128 v[150:153], v128
	ds_read_b128 v[154:157], v128 offset:1024
	ds_read_b128 v[158:161], v181
	ds_read_b128 v[162:165], v181 offset:1024
	s_add_u32 s50, s34, 0x100000
	v_mov_b32_e32 v128, v172
	s_mov_b32 m0, s89
	ds_read_b128 v[166:169], v179 offset:32768
	ds_read_b128 v[184:187], v179 offset:33792
	ds_read_b128 v[188:191], v179 offset:34816
	ds_read_b128 v[192:195], v179 offset:35840
	ds_read_b128 v[196:199], v179 offset:36864
	ds_read_b128 v[200:203], v179 offset:37888
	ds_read_b128 v[204:207], v179 offset:38912
	ds_read_b128 v[208:211], v179 offset:39936
	s_addc_u32 s51, s35, 0
	s_nop 0
	global_load_lds_dwordx4 v128, s[50:51]
	v_mov_b32_e32 v128, v173
	s_mov_b32 m0, s90
	s_nop 0
	global_load_lds_dwordx4 v128, s[50:51]
	s_waitcnt vmcnt(8)
	s_waitcnt lgkmcnt(0)
	s_barrier
	s_setprio 1
	s_waitcnt lgkmcnt(0)
	v_mfma_f32_16x16x32_bf16 v[124:127], v[134:137], v[166:169], v[124:127]
	v_mfma_f32_16x16x32_bf16 v[120:123], v[142:145], v[166:169], v[120:123]
	v_mfma_f32_16x16x32_bf16 v[104:107], v[142:145], v[188:191], v[104:107]
	v_mfma_f32_16x16x32_bf16 v[108:111], v[134:137], v[188:191], v[108:111]
	v_mfma_f32_16x16x32_bf16 v[92:95], v[134:137], v[196:199], v[92:95]
	v_mfma_f32_16x16x32_bf16 v[88:91], v[142:145], v[196:199], v[88:91]
	v_mfma_f32_16x16x32_bf16 v[72:75], v[142:145], v[204:207], v[72:75]
	v_mfma_f32_16x16x32_bf16 v[76:79], v[134:137], v[204:207], v[76:79]
	v_mfma_f32_16x16x32_bf16 v[124:127], v[138:141], v[184:187], v[124:127]
	v_mfma_f32_16x16x32_bf16 v[120:123], v[146:149], v[184:187], v[120:123]
	v_mfma_f32_16x16x32_bf16 v[104:107], v[146:149], v[192:195], v[104:107]
	v_mfma_f32_16x16x32_bf16 v[108:111], v[138:141], v[192:195], v[108:111]
	v_mfma_f32_16x16x32_bf16 v[92:95], v[138:141], v[200:203], v[92:95]
	v_mfma_f32_16x16x32_bf16 v[88:91], v[146:149], v[200:203], v[88:91]
	v_mfma_f32_16x16x32_bf16 v[72:75], v[146:149], v[208:211], v[72:75]
	v_mfma_f32_16x16x32_bf16 v[76:79], v[138:141], v[208:211], v[76:79]
	s_setprio 0
	s_setprio 1
	v_mfma_f32_16x16x32_bf16 v[116:119], v[150:153], v[166:169], v[116:119]
	v_mfma_f32_16x16x32_bf16 v[112:115], v[158:161], v[166:169], v[112:115]
	v_mfma_f32_16x16x32_bf16 v[96:99], v[158:161], v[188:191], v[96:99]
	v_mfma_f32_16x16x32_bf16 v[100:103], v[150:153], v[188:191], v[100:103]
	v_mfma_f32_16x16x32_bf16 v[84:87], v[150:153], v[196:199], v[84:87]
	v_mfma_f32_16x16x32_bf16 v[80:83], v[158:161], v[196:199], v[80:83]
	v_mfma_f32_16x16x32_bf16 v[64:67], v[158:161], v[204:207], v[64:67]
	v_mfma_f32_16x16x32_bf16 v[68:71], v[150:153], v[204:207], v[68:71]
	v_mfma_f32_16x16x32_bf16 v[116:119], v[154:157], v[184:187], v[116:119]
	v_mfma_f32_16x16x32_bf16 v[112:115], v[162:165], v[184:187], v[112:115]
	v_mfma_f32_16x16x32_bf16 v[96:99], v[162:165], v[192:195], v[96:99]
	v_mfma_f32_16x16x32_bf16 v[100:103], v[154:157], v[192:195], v[100:103]
	v_mfma_f32_16x16x32_bf16 v[84:87], v[154:157], v[200:203], v[84:87]
	v_mfma_f32_16x16x32_bf16 v[80:83], v[162:165], v[200:203], v[80:83]
	v_mfma_f32_16x16x32_bf16 v[64:67], v[162:165], v[208:211], v[64:67]
	v_mfma_f32_16x16x32_bf16 v[68:71], v[154:157], v[208:211], v[68:71]
	s_setprio 0
	s_barrier
; #define PG8_LDA(dst, b, h) do { if constexpr (FP8) { _Pragma("unroll") for (int m = 0; m < 4; ++m) dst##8[m] = PG8_LD8(PG8_SA(b, h), aoff, aoff1, m); } \
;         else { _Pragma("unroll") for (int m = 0; m < 4; ++m) _Pragma("unroll") for (int k = 0; k < 2; ++k) dst[m][k] = *(const LAS bf16x8*)(lds + PG8_SA(b, h) + (k ? aoff1 : aoff) + m * 2048); } } while (0)
; #define PG8_LDB(dst, b, h) do { if constexpr (FP8) { dst##8[0] = PG8_LD8(PG8_SB(b, h), boff, boff1, 0); dst##8[1] = PG8_LD8(PG8_SB(b, h), boff, boff1, 1); } \
;         else { _Pragma("unroll") for (int n = 0; n < 2; ++n) _Pragma("unroll") for (int k = 0; k < 2; ++k) dst[n][k] = *(const LAS bf16x8*)(lds + PG8_SB(b, h) + (k ? boff1 : boff) + n * 2048); } } while (0)
; #define PG8_WAIT_V(n) asm volatile("s_waitcnt vmcnt(" #n ")" ::: "memory")
; #define PG8_WAIT_L(n) asm volatile("s_waitcnt lgkmcnt(" #n ")" ::: "memory")
; #define PG8_BAR __builtin_amdgcn_s_barrier()
; #define PG8_SCHED __builtin_amdgcn_sched_barrier(0)
; #define PG8_S1 PG8_STAGE(PG8_SA(1, 1), a1 + hstepA, voffA)
; #define PG8_S3 PG8_STAGE(PG8_SA(0, 1), a2 + hstepA, voffA)
; template <class Epi, class SchedT, bool ALIGN_EPI, bool SP2, bool FP8 = false>
; __device__ __forceinline__ void gemm_phase(LAS unsigned char* lds, const Gemm g, const SchedT& S, const Epi& E, const int wid) {
;     ...
;         for (int t = 0; t < nt; t += 2) {
;             const bool last = (t == nt - 2);
;             const char* a1 = cA + (size_t)(t + 1) * kstep;
;             const char* a2 = last ? nA : cA + (size_t)(t + 2) * kstep; const char* b2 = last ? nB : cB + (size_t)(t + 2) * kstep;
;             const char* a3 = a2 + kstep; const char* b3 = b2 + kstep;
;     ...
;             PG8_LDB(B0, 0, 0); PG8_LDB(B1, 0, 1); PG8_SCHED; PG8_LDA(At, 0, 0); PG8_S1;
;             PG8_WAIT_V(8); PG8_WAIT_L(0); PG8_BAR; PG8_MMAP(0, 0, 0); PG8_BAR; PG8_SCHED;
;             PG8_LDA(At, 0, 1); PG8_S2;
;             PG8_WAIT_V(8); PG8_WAIT_L(0); PG8_BAR; PG8_MMAP(1, 0, 1); PG8_BAR; PG8_SCHED;
;             PG8_LDB(B0, 1, 0); PG8_LDB(B1, 1, 1); PG8_SCHED; PG8_LDA(At, 1, 0); PG8_S3;
;             PG8_WAIT_V(8); PG8_WAIT_L(0); PG8_BAR; PG8_MMAP(0, 1, 0); PG8_BAR; PG8_SCHED;
;             PG8_LDA(At, 1, 1); PG8_S4;
;             PG8_WAIT_V(8); PG8_WAIT_L(0); PG8_BAR; PG8_MMAP(1, 1, 1); PG8_BAR; PG8_SCHED;
	v_mov_b32_e32 v128, v172
	ds_read_b128 v[166:169], v179 offset:49152
	ds_read_b128 v[184:187], v179 offset:50176
	ds_read_b128 v[188:191], v179 offset:51200
	ds_read_b128 v[192:195], v179 offset:52224
	ds_read_b128 v[196:199], v179 offset:53248
	ds_read_b128 v[200:203], v179 offset:54272
	ds_read_b128 v[204:207], v179 offset:55296
	ds_read_b128 v[208:211], v179 offset:56320
	s_add_i32 s16, s16, s86
	v_lshl_add_u64 v[170:171], s[38:39], 0, v[128:129]
	v_lshl_add_u64 v[170:171], v[170:171], 0, s[8:9]
	s_mov_b32 m0, s16
	v_mov_b32_e32 v128, v173
	global_load_lds_dwordx4 v[170:171], off
	s_add_i32 m0, s16, 0x2000
	s_nop 0
	v_lshl_add_u64 v[170:171], s[38:39], 0, v[128:129]
	s_add_u32 s38, s38, 0x100080
	v_lshl_add_u64 v[170:171], v[170:171], 0, s[8:9]
	s_addc_u32 s39, s39, 0
	v_mov_b32_e32 v128, v172
	s_add_i32 s16, s17, s86
	global_load_lds_dwordx4 v[170:171], off
	s_mov_b32 m0, s16
	s_nop 0
	global_load_lds_dwordx4 v128, s[38:39]
	v_mov_b32_e32 v128, v173
	s_add_i32 m0, s16, 0x2000
	s_nop 0
	global_load_lds_dwordx4 v128, s[38:39]
	v_mov_b32_e32 v128, v172
	s_mov_b32 m0, s92
	v_lshl_add_u64 v[170:171], s[34:35], 0, v[128:129]
	v_lshl_add_u64 v[170:171], v[170:171], 0, s[8:9]
	v_mov_b32_e32 v128, v173
	global_load_lds_dwordx4 v[170:171], off
	s_mov_b32 m0, s93
	v_lshl_add_u64 v[170:171], s[34:35], 0, v[128:129]
	v_lshl_add_u64 v[170:171], v[170:171], 0, s[8:9]
	global_load_lds_dwordx4 v[170:171], off
	s_waitcnt vmcnt(8)
	s_waitcnt lgkmcnt(0)
	s_barrier
	s_setprio 1
	s_waitcnt lgkmcnt(0)
	v_mfma_f32_16x16x32_bf16 v[60:63], v[134:137], v[166:169], v[60:63]
	v_mfma_f32_16x16x32_bf16 v[56:59], v[142:145], v[166:169], v[56:59]
	v_mfma_f32_16x16x32_bf16 v[40:43], v[142:145], v[188:191], v[40:43]
	v_mfma_f32_16x16x32_bf16 v[44:47], v[134:137], v[188:191], v[44:47]
	v_mfma_f32_16x16x32_bf16 v[28:31], v[134:137], v[196:199], v[28:31]
	v_mfma_f32_16x16x32_bf16 v[24:27], v[142:145], v[196:199], v[24:27]
	v_mfma_f32_16x16x32_bf16 v[8:11], v[142:145], v[204:207], v[8:11]
	v_mfma_f32_16x16x32_bf16 v[12:15], v[134:137], v[204:207], v[12:15]
	v_mfma_f32_16x16x32_bf16 v[60:63], v[138:141], v[184:187], v[60:63]
	v_mfma_f32_16x16x32_bf16 v[56:59], v[146:149], v[184:187], v[56:59]
	v_mfma_f32_16x16x32_bf16 v[40:43], v[146:149], v[192:195], v[40:43]
	v_mfma_f32_16x16x32_bf16 v[44:47], v[138:141], v[192:195], v[44:47]
	v_mfma_f32_16x16x32_bf16 v[28:31], v[138:141], v[200:203], v[28:31]
	v_mfma_f32_16x16x32_bf16 v[24:27], v[146:149], v[200:203], v[24:27]
	v_mfma_f32_16x16x32_bf16 v[8:11], v[146:149], v[208:211], v[8:11]
	v_mfma_f32_16x16x32_bf16 v[12:15], v[138:141], v[208:211], v[12:15]
	s_setprio 0
	s_setprio 1
	v_mfma_f32_16x16x32_bf16 v[52:55], v[150:153], v[166:169], v[52:55]
	v_mfma_f32_16x16x32_bf16 v[48:51], v[158:161], v[166:169], v[48:51]
	v_mfma_f32_16x16x32_bf16 v[32:35], v[158:161], v[188:191], v[32:35]
	v_mfma_f32_16x16x32_bf16 v[36:39], v[150:153], v[188:191], v[36:39]
	v_mfma_f32_16x16x32_bf16 v[20:23], v[150:153], v[196:199], v[20:23]
	v_mfma_f32_16x16x32_bf16 v[16:19], v[158:161], v[196:199], v[16:19]
	v_mfma_f32_16x16x32_bf16 v[0:3], v[158:161], v[204:207], v[0:3]
	v_mfma_f32_16x16x32_bf16 v[4:7], v[150:153], v[204:207], v[4:7]
	v_mfma_f32_16x16x32_bf16 v[52:55], v[154:157], v[184:187], v[52:55]
	v_mfma_f32_16x16x32_bf16 v[48:51], v[162:165], v[184:187], v[48:51]
	v_mfma_f32_16x16x32_bf16 v[32:35], v[162:165], v[192:195], v[32:35]
	v_mfma_f32_16x16x32_bf16 v[36:39], v[154:157], v[192:195], v[36:39]
	v_mfma_f32_16x16x32_bf16 v[20:23], v[154:157], v[200:203], v[20:23]
	v_mfma_f32_16x16x32_bf16 v[16:19], v[162:165], v[200:203], v[16:19]
	v_mfma_f32_16x16x32_bf16 v[0:3], v[162:165], v[208:211], v[0:3]
	v_mfma_f32_16x16x32_bf16 v[4:7], v[154:157], v[208:211], v[4:7]
	s_setprio 0
	s_barrier
	s_add_u32 s24, s24, 0x100
	s_addc_u32 s25, s25, 0
	s_add_u32 s46, s46, 0x100
	s_addc_u32 s47, s47, 0
	s_cmp_ge_i32 s48, s30
	s_mov_b32 s34, s48
	s_cbranch_scc0 .LBB0_970
	s_and_b64 vcc, exec, s[96:97]
	s_cbranch_vccz .LBB0_973
